# merge GEMM: start offset of the second workgroup half 3 sleeps (about 10 us) instead of 2
# baseline (speedup 1.0000x reference)
; __global__ void __launch_bounds__(NTHREADS, 2) fwd_kernel(Args A) {
;     ...
;         case 4: if (PMASK & 16) { pg8::Gemm g{(const bf16_t*)(ws + WS_Y), wl + WT_BR, Mx, DM, DM, 0, 0}; const bool coop = (ph_hi - ph_lo > 1);
;                   if (last) S.init(NLAT, DM, C.G, C.bid); else if (coop) S.init(NLAT, DM, C.G, C.bid, NCTX, 4); else S.init(MROWS, DM, C.G, C.bid);
;                   pg8::EpiMerge E{(const bf16_t*)(ws + WS_G), (bf16_t*)(ws + WS_MB), (float*)(ws + WS_PB)};
;                   pg8::gemm_phase<pg8::EpiMerge, true>(C.lds, C.tid, g, S, E);
.LBB0_242:
	v_readlane_b32 s100, v249, 56
	s_nop 3
	s_bitcmp1_b32 s100, 3
	s_cbranch_scc0 .Lmerge_nodelay
	s_sleep 127
	s_sleep 127
	s_sleep 127
